# attention loop: back edge rotated so the loop-back barrier is the loop head (counter/branch work moved in front of the barrier, exit path gets its own barrier copy)
# speedup vs baseline: 1.0154x; 1.0096x over previous
; __device__ __forceinline__ int v_st(int k, int c) { const int kk = (k & ~0xC) | ((k & 4) << 1) | ((k & 8) >> 1); return ((kk >> 3) * 4 + (c >> 5)) * 512 + ((kk & 7) * 32 + (c & 31)) * 2; }
; __device__ __forceinline__ int v_rd_base(int lane) { return ((lane & 3) << 3) | (((lane >> 2) & 3) << 6) | (((lane >> 4) & 1) << 5) | (((lane >> 5) & 1) << 8); }
; #define SLOAD(i, k0) do { sr_[i].vs0 = St::ld8(&Vh[(long)((k0) + sr) * LDK + sc]); sr_[i].vs1 = St::ld8(&Vh[(long)((k0) + 32 + sr) * LDK + sc]); \
;     sr_[i].ks0 = St::ld8(&Kh[(long)((k0) + sr) * LDK + sc]); sr_[i].ks1 = St::ld8(&Kh[(long)((k0) + 32 + sr) * LDK + sc]); } while (0)
; #define SWAIT() do { if constexpr (SDEPTH == 2) asm volatile("s_waitcnt vmcnt(4)" ::: "memory"); else asm volatile("s_waitcnt vmcnt(0)" ::: "memory"); } while (0)
; template <typename TQ>
; __device__ __forceinline__ void attn_dense_body(const TQ* __restrict__ Qb, const bf16* __restrict__ Kh, const bf16* __restrict__ Vh,
;                                                 unsigned short* __restrict__ Ob, int seq, char* lds) {
;     ...
;   const int tid = threadIdx.x, wid = tid >> 6, lane = tid & 63, r32 = lane & 31, hi = lane >> 5;
;   bf16* V_lds = (bf16*)lds; bf16* K_lds = (bf16*)(lds + 2 * SHM_V);
;   float* ws = (float*)(lds + 2 * SHM_V + 2 * SHM_K) + wid * 64; float* li_l = ws; float* al_l = ws + 32;
;   float m_reg = -1e30f, l_reg = 0; f32x16 o[4] = {}; bf16x8 qr[8];
;   const TQ* Qw = Qb + (long)(wid * QBLK + r32) * LDQ + hi * 8;
; #pragma unroll
;   for (int d0 = 0; d0 < 8; ++d0) qr[d0] = SQ::tobf(SQ::ld8(Qw + d0 * 16));
;   const int sr = tid >> 4, sc = (tid & 15) * 8, vst0 = v_st(sr, sc), vst1 = v_st(32 + sr, sc);
;   const int vb0 = (int)(uintptr_t)V_lds + v_rd_base(lane);
;   struct { typename St::T vs0, vs1, ks0, ks1; } sr_[SDEPTH];
;     ...
;   f32x16 pA0, pA1, pB0, pB1; float mnA, mnB, alA, alB; bf16x8 pa0, pa1, pa2, pa3; const int NT = seq / KVBLK;
;   constexpr int SE = 0, SO = SDEPTH - 1;
;   SLOAD(SE, 0); asm volatile("s_waitcnt vmcnt(0)" ::: "memory"); SWRITE(0, SE); __syncthreads();
;   qkt(pA0, pA1, K_lds, qr, r32, hi); partialSM(pA0, pA1, m_reg, mnA, alA);
;   SLOAD(SO, KVBLK); if constexpr (SDEPTH == 2) { if (2 < NT) SLOAD(SE, 2 * KVBLK); }
;   SWAIT(); SWRITE(1, SO); __syncthreads();
.LBB0_1585:
	s_bfe_u32 s34, s33, 0x10007
	s_bfe_u32 s4, s33, 0x20005
	s_ashr_i32 s65, s33, 8
	s_lshl_b32 s5, s34, 2
	s_or_b32 s63, s5, s4
	s_lshl_b32 s4, s65, 3
	s_or_b32 s4, s63, s4
	s_ashr_i32 s5, s4, 31
	s_lshl_b32 s35, s33, 8
	s_and_b32 s66, s35, 0x1f00
	s_lshl_b64 s[4:5], s[4:5], 21
	s_add_u32 s4, s47, s4
	s_addc_u32 s5, s64, s5
	s_lshl_b32 s35, s66, 8
	s_add_u32 s38, s4, s35
	s_addc_u32 s39, s5, 0
	s_lshl_b32 s4, s65, 1
	s_or_b32 s5, s4, s34
	s_mul_hi_i32 s4, s5, 0x210000
	s_mul_i32 s5, s5, 0x210000
	s_add_u32 s34, s24, s5
	s_addc_u32 s35, s25, s4
	s_add_u32 s36, s26, s5
	s_addc_u32 s37, s27, s4
	global_load_dwordx4 v[2:5], v189, s[36:37]
	global_load_dwordx4 v[6:9], v190, s[36:37]
	global_load_dwordx4 v[10:13], v189, s[34:35]
	global_load_dwordx4 v[14:17], v190, s[34:35]
	v_mov_b32_e32 v177, v167
	v_lshl_add_u64 v[18:19], s[38:39], 0, v[176:177]
	v_lshl_add_u64 v[18:19], v[18:19], 0, v[178:179]
	global_load_dwordx4 v[126:129], v[18:19], off
	global_load_dwordx4 v[122:125], v[18:19], off offset:32
	global_load_dwordx4 v[118:121], v[18:19], off offset:64
	global_load_dwordx4 v[114:117], v[18:19], off offset:96
	global_load_dwordx4 v[110:113], v[18:19], off offset:128
	global_load_dwordx4 v[106:109], v[18:19], off offset:160
	global_load_dwordx4 v[102:105], v[18:19], off offset:192
	global_load_dwordx4 v[98:101], v[18:19], off offset:224
	s_waitcnt vmcnt(0)
	s_movk_i32 s67, 0x100
	s_mov_b32 s68, 1
	v_mov_b32_e32 v175, 0
	s_waitcnt vmcnt(11)
	ds_write_b128 v191, v[2:5]
	s_waitcnt vmcnt(10)
	ds_write_b128 v192, v[6:9]
	s_waitcnt vmcnt(9)
	ds_write_b128 v193, v[10:13] offset:32768
	s_waitcnt vmcnt(8)
	ds_write_b128 v194, v[14:17] offset:32768
	s_waitcnt lgkmcnt(0)
	s_barrier
	ds_read_b128 v[2:5], v195 offset:32768
	ds_read_b128 v[6:9], v195 offset:40960
	s_waitcnt vmcnt(7) lgkmcnt(1)
	v_mfma_f32_32x32x16_bf16 v[34:49], v[2:5], v[126:129], 0
	s_waitcnt lgkmcnt(0)
	v_mfma_f32_32x32x16_bf16 v[50:65], v[6:9], v[126:129], 0
	ds_read_b128 v[2:5], v196 offset:32768
	ds_read_b128 v[6:9], v196 offset:40960
	s_waitcnt vmcnt(6) lgkmcnt(1)
	v_mfma_f32_32x32x16_bf16 v[34:49], v[2:5], v[122:125], v[34:49]
	s_waitcnt lgkmcnt(0)
	v_mfma_f32_32x32x16_bf16 v[50:65], v[6:9], v[122:125], v[50:65]
	ds_read_b128 v[2:5], v197 offset:32768
	ds_read_b128 v[6:9], v197 offset:40960
	s_waitcnt vmcnt(5) lgkmcnt(1)
	v_mfma_f32_32x32x16_bf16 v[34:49], v[2:5], v[118:121], v[34:49]
	s_waitcnt lgkmcnt(0)
	v_mfma_f32_32x32x16_bf16 v[50:65], v[6:9], v[118:121], v[50:65]
	ds_read_b128 v[2:5], v198 offset:32768
	ds_read_b128 v[6:9], v198 offset:40960
	s_waitcnt vmcnt(4) lgkmcnt(1)
	v_mfma_f32_32x32x16_bf16 v[34:49], v[2:5], v[114:117], v[34:49]
	s_waitcnt lgkmcnt(0)
	v_mfma_f32_32x32x16_bf16 v[50:65], v[6:9], v[114:117], v[50:65]
	ds_read_b128 v[2:5], v199 offset:32768
	ds_read_b128 v[6:9], v199 offset:40960
	s_waitcnt vmcnt(3) lgkmcnt(1)
	v_mfma_f32_32x32x16_bf16 v[34:49], v[2:5], v[110:113], v[34:49]
	s_waitcnt lgkmcnt(0)
	v_mfma_f32_32x32x16_bf16 v[50:65], v[6:9], v[110:113], v[50:65]
	ds_read_b128 v[2:5], v200 offset:32768
	ds_read_b128 v[6:9], v200 offset:40960
	s_waitcnt vmcnt(2) lgkmcnt(1)
	v_mfma_f32_32x32x16_bf16 v[34:49], v[2:5], v[106:109], v[34:49]
	s_waitcnt lgkmcnt(0)
	v_mfma_f32_32x32x16_bf16 v[50:65], v[6:9], v[106:109], v[50:65]
	ds_read_b128 v[2:5], v201 offset:32768
	ds_read_b128 v[6:9], v201 offset:40960
	global_load_dwordx4 v[66:69], v205, s[36:37]
	global_load_dwordx4 v[70:73], v204, s[36:37]
	global_load_dwordx4 v[74:77], v204, s[34:35]
	global_load_dwordx4 v[78:81], v205, s[34:35]
	ds_read_b128 v[18:21], v202 offset:32768
	ds_read_b128 v[82:85], v202 offset:40960
	global_load_dwordx4 v[130:133], v206, s[36:37]
	global_load_dwordx4 v[134:137], v206, s[34:35]
	global_load_dwordx4 v[142:145], v207, s[36:37]
	global_load_dwordx4 v[138:141], v207, s[34:35]
	s_waitcnt vmcnt(4)
	s_waitcnt vmcnt(9) lgkmcnt(3)
	v_mfma_f32_32x32x16_bf16 v[34:49], v[2:5], v[102:105], v[34:49]
	s_waitcnt vmcnt(6)
	ds_write_b128 v191, v[70:73] offset:16384
	ds_write_b128 v192, v[66:69] offset:16384
	s_waitcnt vmcnt(5)
	ds_write_b128 v193, v[74:77] offset:49152
	s_waitcnt vmcnt(4)
	ds_write_b128 v194, v[78:81] offset:49152
	s_waitcnt lgkmcnt(6)
	v_mfma_f32_32x32x16_bf16 v[50:65], v[6:9], v[102:105], v[50:65]
	v_mov_b64_e32 v[2:3], s[8:9]
	v_mov_b64_e32 v[16:17], s[22:23]
	v_mov_b64_e32 v[4:5], s[10:11]
	v_mov_b64_e32 v[6:7], s[12:13]
	v_mov_b64_e32 v[8:9], s[14:15]
	v_mov_b64_e32 v[10:11], s[16:17]
	v_mov_b64_e32 v[12:13], s[18:19]
	s_waitcnt lgkmcnt(5)
	v_mfma_f32_32x32x16_bf16 v[34:49], v[18:21], v[98:101], v[34:49]
	v_mov_b64_e32 v[14:15], s[20:21]
	v_mov_b64_e32 v[32:33], v[16:17]
	v_mov_b64_e32 v[30:31], v[14:15]
	v_mov_b64_e32 v[28:29], v[12:13]
	v_mov_b64_e32 v[26:27], v[10:11]
	v_mov_b64_e32 v[24:25], v[8:9]
	v_mov_b64_e32 v[22:23], v[6:7]
	s_waitcnt lgkmcnt(4)
; __device__ __forceinline__ void partialSM(f32x16& p0, f32x16& p1, float& m_reg, float& mn, float& alpha) {
;   constexpr float C = SCALE * 1.4426950408889634f;
;   float pmax = p0[0]; for (int r = 1; r < 16; ++r) pmax = fmaxf(pmax, p0[r]); for (int r = 0; r < 16; ++r) pmax = fmaxf(pmax, p1[r]);
;   { auto rr = __builtin_amdgcn_permlane32_swap(__float_as_uint(pmax), __float_as_uint(pmax), false, false);
;     pmax = fmaxf(__uint_as_float(rr[0]), __uint_as_float(rr[1])); }
;   if (__builtin_expect(__all(pmax - m_reg <= THR / SCALE), 1)) { mn = m_reg; alpha = 1.f; }
;   else { mn = fmaxf(m_reg, pmax); alpha = __builtin_amdgcn_exp2f((m_reg - mn) * C); m_reg = mn; }
;   float mnC = -mn * C;
;   for (int r = 0; r < 16; ++r) p0[r] = fmaf(p0[r], C, mnC); for (int r = 0; r < 16; ++r) p1[r] = fmaf(p1[r], C, mnC);
;   for (int r = 0; r < 16; ++r) p0[r] = __builtin_amdgcn_exp2f(p0[r]);
; }
; __device__ __forceinline__ void finishSM(f32x16& p0, f32x16& p1, float alpha, float& l_reg, bf16x8& pa0, bf16x8& pa1, bf16x8& pa2, bf16x8& pa3) {
;   for (int r = 0; r < 16; ++r) p1[r] = __builtin_amdgcn_exp2f(p1[r]);
;   float ps = 0; for (int r = 0; r < 16; ++r) ps += p0[r]; for (int r = 0; r < 16; ++r) ps += p1[r];
;   { auto rr = __builtin_amdgcn_permlane32_swap(__float_as_uint(ps), __float_as_uint(ps), false, false);
;     ps = __uint_as_float(rr[0]) + __uint_as_float(rr[1]); }
;   l_reg = l_reg * alpha + ps;
;     ...
;   PK4(p0, 0, pa0); PK4(p0, 8, pa1); PK4(p1, 0, pa2); PK4(p1, 8, pa3);
;     ...
; }
; __device__ __forceinline__ void qkt(f32x16& p0, f32x16& p1, const bf16* Ks, const bf16x8* qr, int r32, int hi) {
;   p0 = f32x16{}; p1 = f32x16{};
;   for (int d0 = 0; d0 < 8; ++d0) { int cb = (d0 * 16 + hi * 8) * 2;
;     bf16x8 b0 = *reinterpret_cast<const bf16x8*>((const char*)Ks + KSWZ(r32, cb));
;     bf16x8 b1 = *reinterpret_cast<const bf16x8*>((const char*)Ks + KSWZ(32 + r32, cb));
;     p0 = __builtin_amdgcn_mfma_f32_32x32x16_bf16(b0, qr[d0], p0, 0, 0, 0);
;     p1 = __builtin_amdgcn_mfma_f32_32x32x16_bf16(b1, qr[d0], p1, 0, 0, 0); }
; template <typename TQ>
; __device__ __forceinline__ void attn_dense_body(const TQ* __restrict__ Qb, const bf16* __restrict__ Kh, const bf16* __restrict__ Vh,
;                                                 unsigned short* __restrict__ Ob, int seq, char* lds) {
;     ...
;   qkt(pA0, pA1, K_lds, qr, r32, hi); partialSM(pA0, pA1, m_reg, mnA, alA);
	v_mfma_f32_32x32x16_bf16 v[50:65], v[82:85], v[98:101], v[50:65]
	s_nop 2
	v_max_f32_e32 v82, v35, v35
	v_max_f32_e32 v83, v34, v34
	v_max_f32_e32 v82, v83, v82
	v_max3_f32 v82, v82, v36, v37
	v_max3_f32 v82, v82, v38, v39
	v_max3_f32 v82, v82, v40, v41
	v_max3_f32 v82, v82, v42, v43
	v_max3_f32 v82, v82, v44, v45
	v_max3_f32 v82, v82, v46, v47
	v_max3_f32 v66, v82, v48, v49
	v_max3_f32 v66, v66, v50, v51
	v_max3_f32 v66, v66, v52, v53
	v_max3_f32 v66, v66, v54, v55
	v_max3_f32 v66, v66, v56, v57
	v_max3_f32 v66, v66, v58, v59
	v_max3_f32 v66, v66, v60, v61
	v_max3_f32 v66, v66, v62, v63
	v_max3_f32 v66, v66, v64, v65
	v_mov_b32_e32 v67, v66
	s_nop 1
	v_permlane32_swap_b32_e32 v66, v67
	v_max_f32_e32 v67, v67, v67
	v_max_f32_e32 v66, v66, v66
	v_max_f32_e32 v66, v66, v67
	v_add_f32_e32 v67, 0x7149f2ca, v66
	v_cmp_ge_f32_e32 vcc, s48, v67
	s_cmp_eq_u64 vcc, exec
	v_max_f32_e32 v66, 0xf149f2ca, v66
	s_cselect_b64 vcc, -1, 0
	v_sub_f32_e32 v67, 0xf149f2ca, v66
	v_cndmask_b32_e32 v208, v66, v203, vcc
	v_mul_f32_e32 v67, 0x3e0293ee, v67
	v_mul_f32_e32 v66, 0xbe0293ee, v208
	v_exp_f32_e32 v67, v67
	v_mov_b32_e32 v68, v66
	v_fmamk_f32 v34, v34, 0x3e0293ee, v66
	v_fmamk_f32 v35, v35, 0x3e0293ee, v66
	v_fmamk_f32 v36, v36, 0x3e0293ee, v66
	v_fmamk_f32 v37, v37, 0x3e0293ee, v66
	v_fmamk_f32 v38, v38, 0x3e0293ee, v66
	v_fmamk_f32 v39, v39, 0x3e0293ee, v66
	v_fmamk_f32 v40, v40, 0x3e0293ee, v66
	v_fmamk_f32 v41, v41, 0x3e0293ee, v66
	v_fmamk_f32 v42, v42, 0x3e0293ee, v66
	v_fmamk_f32 v43, v43, 0x3e0293ee, v66
	v_fmamk_f32 v44, v44, 0x3e0293ee, v66
	v_fmamk_f32 v45, v45, 0x3e0293ee, v66
	v_fmamk_f32 v46, v46, 0x3e0293ee, v66
	v_fmamk_f32 v47, v47, 0x3e0293ee, v66
	v_fmamk_f32 v48, v48, 0x3e0293ee, v66
	v_fmac_f32_e32 v68, 0x3e0293ee, v49
	v_exp_f32_e32 v224, v34
	v_exp_f32_e32 v226, v35
	v_exp_f32_e32 v222, v36
	v_exp_f32_e32 v225, v37
	v_exp_f32_e32 v164, v38
	v_exp_f32_e32 v223, v39
	v_exp_f32_e32 v220, v40
	v_exp_f32_e32 v221, v41
	v_exp_f32_e32 v217, v42
	v_exp_f32_e32 v219, v43
	v_exp_f32_e32 v216, v44
	v_exp_f32_e32 v218, v45
	v_exp_f32_e32 v213, v46
	v_exp_f32_e32 v215, v47
	v_exp_f32_e32 v212, v48
	v_exp_f32_e32 v214, v68
	s_add_u32 s38, s90, s5
	v_pk_fma_f32 v[152:153], v[64:65], s[30:31], v[66:67] op_sel_hi:[1,0,0]
	v_pk_fma_f32 v[158:159], v[62:63], s[30:31], v[66:67] op_sel_hi:[1,0,0]
	v_pk_fma_f32 v[160:161], v[60:61], s[30:31], v[66:67] op_sel_hi:[1,0,0]
	v_pk_fma_f32 v[146:147], v[58:59], s[30:31], v[66:67] op_sel_hi:[1,0,0]
	v_pk_fma_f32 v[148:149], v[56:57], s[30:31], v[66:67] op_sel_hi:[1,0,0]
	v_pk_fma_f32 v[150:151], v[54:55], s[30:31], v[66:67] op_sel_hi:[1,0,0]
	v_pk_fma_f32 v[154:155], v[52:53], s[30:31], v[66:67] op_sel_hi:[1,0,0]
	v_pk_fma_f32 v[156:157], v[50:51], s[30:31], v[66:67] op_sel_hi:[1,0,0]
	v_mov_b64_e32 v[64:65], v[16:17]
	v_mov_b64_e32 v[48:49], v[16:17]
	v_mov_b64_e32 v[20:21], v[4:5]
	v_mov_b64_e32 v[18:19], v[2:3]
	s_addc_u32 s39, s91, s4
	v_cndmask_b32_e64 v177, v67, 1.0, vcc
	v_mov_b64_e32 v[62:63], v[14:15]
	v_mov_b64_e32 v[60:61], v[12:13]
	v_mov_b64_e32 v[58:59], v[10:11]
	v_mov_b64_e32 v[56:57], v[8:9]
	v_mov_b64_e32 v[54:55], v[6:7]
	v_mov_b64_e32 v[52:53], v[4:5]
	v_mov_b64_e32 v[50:51], v[2:3]
	v_mov_b64_e32 v[46:47], v[14:15]
	v_mov_b64_e32 v[44:45], v[12:13]
	v_mov_b64_e32 v[42:43], v[10:11]
	v_mov_b64_e32 v[40:41], v[8:9]
	v_mov_b64_e32 v[38:39], v[6:7]
	v_mov_b64_e32 v[36:37], v[4:5]
	v_mov_b64_e32 v[34:35], v[2:3]
	s_waitcnt lgkmcnt(0)
.Lattn_head:
	s_barrier
.LBB0_1586:
	ds_read_b128 v[66:69], v195 offset:49152
	ds_read_b128 v[70:73], v195 offset:57344
	ds_read_b128 v[228:231], v196 offset:49152
	ds_read_b128 v[232:235], v196 offset:57344
	v_add_f32_e32 v162, 0, v224
	v_add_f32_e32 v162, v226, v162
	v_add_f32_e32 v162, v222, v162
	v_add_f32_e32 v162, v225, v162
	v_add_f32_e32 v162, v164, v162
	s_waitcnt lgkmcnt(3)
	v_mfma_f32_32x32x16_bf16 v[82:97], v[66:69], v[126:129], 0
	v_add_f32_e32 v162, v223, v162
	v_add_f32_e32 v162, v220, v162
	v_add_f32_e32 v162, v221, v162
	v_add_f32_e32 v162, v217, v162
	v_add_f32_e32 v162, v219, v162
	s_waitcnt lgkmcnt(2)
	v_mfma_f32_32x32x16_bf16 v[66:81], v[70:73], v[126:129], 0
	v_add_f32_e32 v162, v216, v162
	v_add_f32_e32 v162, v218, v162
	v_exp_f32_e32 v156, v156
	v_add_f32_e32 v162, v213, v162
	v_exp_f32_e32 v157, v157
	s_waitcnt lgkmcnt(1)
	v_mfma_f32_32x32x16_bf16 v[82:97], v[228:231], v[122:125], v[82:97]
	v_add_f32_e32 v162, v215, v162
	v_exp_f32_e32 v154, v154
	v_add_f32_e32 v162, v212, v162
	v_exp_f32_e32 v155, v155
	v_add_f32_e32 v162, v214, v162
	s_waitcnt lgkmcnt(0)
	v_mfma_f32_32x32x16_bf16 v[66:81], v[232:235], v[122:125], v[66:81]
	ds_read_b128 v[228:231], v197 offset:49152
	ds_read_b128 v[232:235], v197 offset:57344
	v_exp_f32_e32 v150, v150
	v_add_f32_e32 v162, v156, v162
	v_exp_f32_e32 v151, v151
	v_add_f32_e32 v162, v157, v162
	v_exp_f32_e32 v148, v148
	s_waitcnt lgkmcnt(1)
	v_mfma_f32_32x32x16_bf16 v[82:97], v[228:231], v[118:121], v[82:97]
	v_add_f32_e32 v162, v154, v162
	v_exp_f32_e32 v149, v149
	v_add_f32_e32 v162, v155, v162
	v_exp_f32_e32 v146, v146
	v_add_f32_e32 v162, v150, v162
	s_waitcnt lgkmcnt(0)
	v_mfma_f32_32x32x16_bf16 v[66:81], v[232:235], v[118:121], v[66:81]
	ds_read_b128 v[228:231], v198 offset:49152
	ds_read_b128 v[232:235], v198 offset:57344
	v_exp_f32_e32 v147, v147
	v_add_f32_e32 v162, v151, v162
	v_exp_f32_e32 v160, v160
	v_add_f32_e32 v162, v148, v162
	v_exp_f32_e32 v161, v161
	s_waitcnt lgkmcnt(1)
	v_mfma_f32_32x32x16_bf16 v[82:97], v[228:231], v[114:117], v[82:97]
	v_add_f32_e32 v162, v149, v162
	v_exp_f32_e32 v158, v158
	v_add_f32_e32 v162, v146, v162
	v_exp_f32_e32 v159, v159
	v_add_f32_e32 v162, v147, v162
	s_waitcnt lgkmcnt(0)
; __device__ __forceinline__ void finishSM(f32x16& p0, f32x16& p1, float alpha, float& l_reg, bf16x8& pa0, bf16x8& pa1, bf16x8& pa2, bf16x8& pa3) {
;   for (int r = 0; r < 16; ++r) p1[r] = __builtin_amdgcn_exp2f(p1[r]);
;   float ps = 0; for (int r = 0; r < 16; ++r) ps += p0[r]; for (int r = 0; r < 16; ++r) ps += p1[r];
;   { auto rr = __builtin_amdgcn_permlane32_swap(__float_as_uint(ps), __float_as_uint(ps), false, false);
;     ps = __uint_as_float(rr[0]) + __uint_as_float(rr[1]); }
;   l_reg = l_reg * alpha + ps;
;     ...
;   PK4(p0, 0, pa0); PK4(p0, 8, pa1); PK4(p1, 0, pa2); PK4(p1, 8, pa3);
;     ...
; }
; __device__ __forceinline__ void qkt(f32x16& p0, f32x16& p1, const bf16* Ks, const bf16x8* qr, int r32, int hi) {
;   p0 = f32x16{}; p1 = f32x16{};
;   for (int d0 = 0; d0 < 8; ++d0) { int cb = (d0 * 16 + hi * 8) * 2;
;     bf16x8 b0 = *reinterpret_cast<const bf16x8*>((const char*)Ks + KSWZ(r32, cb));
;     bf16x8 b1 = *reinterpret_cast<const bf16x8*>((const char*)Ks + KSWZ(32 + r32, cb));
;     p0 = __builtin_amdgcn_mfma_f32_32x32x16_bf16(b0, qr[d0], p0, 0, 0, 0);
;     p1 = __builtin_amdgcn_mfma_f32_32x32x16_bf16(b1, qr[d0], p1, 0, 0, 0); }
; }
; __device__ __forceinline__ int v_st(int k, int c) { const int kk = (k & ~0xC) | ((k & 4) << 1) | ((k & 8) >> 1); return ((kk >> 3) * 4 + (c >> 5)) * 512 + ((kk & 7) * 32 + (c & 31)) * 2; }
; __device__ __forceinline__ int v_rd_base(int lane) { return ((lane & 3) << 3) | (((lane >> 2) & 3) << 6) | (((lane >> 4) & 1) << 5) | (((lane >> 5) & 1) << 8); }
; template <int OFF> __device__ __forceinline__ s16x4 tr_read(int vb) {
;   s16x4 r; asm volatile("ds_read_b64_tr_b16 %0, %1 offset:%2" : "=&v"(r) : "v"(vb), "i"(OFF) : "memory"); return r;
; }
; template <int D0> __device__ __forceinline__ void pv_one(f32x16& od, int vb, bf16x8 pa0, bf16x8 pa1, bf16x8 pa2, bf16x8 pa3) {
;   const s16x4 l0 = tr_read<v_rd_off(D0, 0, 0)>(vb), h0 = tr_read<v_rd_off(D0, 0, 1)>(vb), l1 = tr_read<v_rd_off(D0, 1, 0)>(vb), h1 = tr_read<v_rd_off(D0, 1, 1)>(vb);
;   const s16x4 l2 = tr_read<v_rd_off(D0, 2, 0)>(vb), h2 = tr_read<v_rd_off(D0, 2, 1)>(vb), l3 = tr_read<v_rd_off(D0, 3, 0)>(vb), h3 = tr_read<v_rd_off(D0, 3, 1)>(vb);
;   asm volatile("s_waitcnt lgkmcnt(0)" ::: "memory"); SBAR();
;     ...
;   od = __builtin_amdgcn_mfma_f32_32x32x16_bf16(pa0, PK(l0, h0), od, 0, 0, 0);
;   od = __builtin_amdgcn_mfma_f32_32x32x16_bf16(pa1, PK(l1, h1), od, 0, 0, 0);
	v_mfma_f32_32x32x16_bf16 v[66:81], v[232:235], v[114:117], v[66:81]
	ds_read_b128 v[228:231], v199 offset:49152
	ds_read_b128 v[232:235], v199 offset:57344
	v_exp_f32_e32 v152, v152
	v_add_f32_e32 v162, v160, v162
	v_exp_f32_e32 v153, v153
	v_add_f32_e32 v162, v161, v162
	v_add_f32_e32 v162, v158, v162
	s_waitcnt lgkmcnt(1)
	v_mfma_f32_32x32x16_bf16 v[82:97], v[228:231], v[110:113], v[82:97]
	v_add_f32_e32 v162, v159, v162
	v_add_f32_e32 v162, v152, v162
	v_add_f32_e32 v209, v153, v162
	v_mov_b32_e32 v210, v209
	s_nop 1
	v_permlane32_swap_b32_e32 v209, v210
	s_waitcnt lgkmcnt(0)
	v_mfma_f32_32x32x16_bf16 v[66:81], v[232:235], v[110:113], v[66:81]
	ds_read_b128 v[228:231], v200 offset:49152
	ds_read_b128 v[232:235], v200 offset:57344
	v_cvt_pk_bf16_f32 v162, v224, v226
	v_cvt_pk_bf16_f32 v163, v222, v225
	v_cvt_pk_bf16_f32 v164, v164, v223
	v_cvt_pk_bf16_f32 v165, v220, v221
	v_cvt_pk_bf16_f32 v220, v217, v219
	s_waitcnt lgkmcnt(1)
	v_mfma_f32_32x32x16_bf16 v[82:97], v[228:231], v[106:109], v[82:97]
	v_cvt_pk_bf16_f32 v221, v216, v218
	v_permlane32_swap_b32_e32 v162, v164
	v_permlane32_swap_b32_e32 v163, v165
	v_cvt_pk_bf16_f32 v222, v213, v215
	v_cvt_pk_bf16_f32 v223, v212, v214
	s_waitcnt lgkmcnt(0)
	v_mfma_f32_32x32x16_bf16 v[66:81], v[232:235], v[106:109], v[66:81]
	ds_read_b128 v[228:231], v201 offset:49152
	ds_read_b128 v[232:235], v201 offset:57344
	v_cvt_pk_bf16_f32 v212, v156, v157
	v_cvt_pk_bf16_f32 v213, v154, v155
	v_cvt_pk_bf16_f32 v214, v150, v151
	v_cvt_pk_bf16_f32 v215, v148, v149
	v_cvt_pk_bf16_f32 v216, v146, v147
	s_waitcnt lgkmcnt(1)
	v_mfma_f32_32x32x16_bf16 v[82:97], v[228:231], v[102:105], v[82:97]
	v_cvt_pk_bf16_f32 v217, v160, v161
	v_cvt_pk_bf16_f32 v218, v158, v159
	v_cvt_pk_bf16_f32 v219, v152, v153
	v_permlane32_swap_b32_e32 v220, v222
	v_permlane32_swap_b32_e32 v221, v223
	s_waitcnt lgkmcnt(0)
	v_mfma_f32_32x32x16_bf16 v[66:81], v[232:235], v[102:105], v[66:81]
	ds_read_b128 v[228:231], v202 offset:49152
	ds_read_b128 v[232:235], v202 offset:57344
	v_permlane32_swap_b32_e32 v212, v214
	v_permlane32_swap_b32_e32 v213, v215
	v_permlane32_swap_b32_e32 v216, v218
	v_permlane32_swap_b32_e32 v217, v219
	s_waitcnt lgkmcnt(1)
	v_mfma_f32_32x32x16_bf16 v[82:97], v[228:231], v[98:101], v[82:97]
	s_waitcnt lgkmcnt(0)
	v_mfma_f32_32x32x16_bf16 v[66:81], v[232:235], v[98:101], v[66:81]
	s_add_u32 s98, s38, s49
	s_addc_u32 s99, s39, 0
	s_add_u32 s100, s38, s52
	s_addc_u32 s101, s39, 0
	global_load_dwordx4 v[146:149], v170, s[98:99]
	global_load_dwordx4 v[150:153], v172, s[98:99]
	global_load_dwordx4 v[154:157], v170, s[100:101]
	global_load_dwordx4 v[158:161], v172, s[100:101]
	ds_read_b64_tr_b16 v[224:225], v185 offset:0
	ds_read_b64_tr_b16 v[226:227], v185 offset:0x800
	ds_read_b64_tr_b16 v[228:229], v185 offset:0x1000
	ds_read_b64_tr_b16 v[230:231], v185 offset:0x1800
	ds_read_b64_tr_b16 v[232:233], v185 offset:0x2000
	ds_read_b64_tr_b16 v[234:235], v185 offset:0x2800
	ds_read_b64_tr_b16 v[236:237], v185 offset:0x3000
	ds_read_b64_tr_b16 v[238:239], v185 offset:0x3800
	s_waitcnt lgkmcnt(0)
	s_nop 0
	v_mfma_f32_32x32x16_bf16 v[2:17], v[162:165], v[224:227], v[2:17]
	v_max_f32_e32 v248, v83, v83
	v_max_f32_e32 v249, v82, v82
	v_max_f32_e32 v248, v249, v248
	v_max3_f32 v248, v248, v84, v85
	v_max3_f32 v248, v248, v86, v87
	ds_read_b64_tr_b16 v[224:225], v185 offset:0x200
	ds_read_b64_tr_b16 v[226:227], v185 offset:0xa00
	v_mfma_f32_32x32x16_bf16 v[2:17], v[220:223], v[228:231], v[2:17]
	v_max3_f32 v248, v248, v88, v89
	v_max3_f32 v248, v248, v90, v91
	v_max3_f32 v248, v248, v92, v93
	v_max3_f32 v248, v248, v94, v95
	v_max3_f32 v248, v248, v96, v97
	ds_read_b64_tr_b16 v[228:229], v185 offset:0x1200
	ds_read_b64_tr_b16 v[230:231], v185 offset:0x1a00
	v_mfma_f32_32x32x16_bf16 v[2:17], v[212:215], v[232:235], v[2:17]
	v_max3_f32 v248, v248, v66, v67
	v_max3_f32 v248, v248, v68, v69
	v_max3_f32 v248, v248, v70, v71
	v_max3_f32 v248, v248, v72, v73
	v_max3_f32 v248, v248, v74, v75
	ds_read_b64_tr_b16 v[232:233], v185 offset:0x2200
	ds_read_b64_tr_b16 v[234:235], v185 offset:0x2a00
	ds_read_b64_tr_b16 v[240:241], v185 offset:0x3200
	ds_read_b64_tr_b16 v[242:243], v185 offset:0x3a00
	s_waitcnt lgkmcnt(0)
; __device__ __forceinline__ void partialSM(f32x16& p0, f32x16& p1, float& m_reg, float& mn, float& alpha) {
;   constexpr float C = SCALE * 1.4426950408889634f;
;   float pmax = p0[0]; for (int r = 1; r < 16; ++r) pmax = fmaxf(pmax, p0[r]); for (int r = 0; r < 16; ++r) pmax = fmaxf(pmax, p1[r]);
;   { auto rr = __builtin_amdgcn_permlane32_swap(__float_as_uint(pmax), __float_as_uint(pmax), false, false);
;     pmax = fmaxf(__uint_as_float(rr[0]), __uint_as_float(rr[1])); }
;   if (__builtin_expect(__all(pmax - m_reg <= THR / SCALE), 1)) { mn = m_reg; alpha = 1.f; }
;   else { mn = fmaxf(m_reg, pmax); alpha = __builtin_amdgcn_exp2f((m_reg - mn) * C); m_reg = mn; }
;   float mnC = -mn * C;
;   for (int r = 0; r < 16; ++r) p0[r] = fmaf(p0[r], C, mnC); for (int r = 0; r < 16; ++r) p1[r] = fmaf(p1[r], C, mnC);
;   for (int r = 0; r < 16; ++r) p0[r] = __builtin_amdgcn_exp2f(p0[r]);
; }
; __device__ __forceinline__ void finishSM(f32x16& p0, f32x16& p1, float alpha, float& l_reg, bf16x8& pa0, bf16x8& pa1, bf16x8& pa2, bf16x8& pa3) {
;   for (int r = 0; r < 16; ++r) p1[r] = __builtin_amdgcn_exp2f(p1[r]);
;   float ps = 0; for (int r = 0; r < 16; ++r) ps += p0[r]; for (int r = 0; r < 16; ++r) ps += p1[r];
;   { auto rr = __builtin_amdgcn_permlane32_swap(__float_as_uint(ps), __float_as_uint(ps), false, false);
;     ps = __uint_as_float(rr[0]) + __uint_as_float(rr[1]); }
;   l_reg = l_reg * alpha + ps;
;     ...
;   PK4(p0, 0, pa0); PK4(p0, 8, pa1); PK4(p1, 0, pa2); PK4(p1, 8, pa3);
;     ...
; }
; __device__ __forceinline__ void qkt(f32x16& p0, f32x16& p1, const bf16* Ks, const bf16x8* qr, int r32, int hi) {
;   p0 = f32x16{}; p1 = f32x16{};
;   for (int d0 = 0; d0 < 8; ++d0) { int cb = (d0 * 16 + hi * 8) * 2;
;     bf16x8 b0 = *reinterpret_cast<const bf16x8*>((const char*)Ks + KSWZ(r32, cb));
;     bf16x8 b1 = *reinterpret_cast<const bf16x8*>((const char*)Ks + KSWZ(32 + r32, cb));
;     p0 = __builtin_amdgcn_mfma_f32_32x32x16_bf16(b0, qr[d0], p0, 0, 0, 0);
;     p1 = __builtin_amdgcn_mfma_f32_32x32x16_bf16(b1, qr[d0], p1, 0, 0, 0); }
; }
; __device__ __forceinline__ int v_st(int k, int c) { const int kk = (k & ~0xC) | ((k & 4) << 1) | ((k & 8) >> 1); return ((kk >> 3) * 4 + (c >> 5)) * 512 + ((kk & 7) * 32 + (c & 31)) * 2; }
; __device__ __forceinline__ int v_rd_base(int lane) { return ((lane & 3) << 3) | (((lane >> 2) & 3) << 6) | (((lane >> 4) & 1) << 5) | (((lane >> 5) & 1) << 8); }
	v_mfma_f32_32x32x16_bf16 v[2:17], v[216:219], v[236:239], v[2:17]
	v_max3_f32 v248, v248, v76, v77
	v_max3_f32 v248, v248, v78, v79
	v_max3_f32 v248, v248, v80, v81
	v_mov_b32_e32 v249, v248
	s_nop 1
	v_mfma_f32_32x32x16_bf16 v[18:33], v[162:165], v[224:227], v[18:33]
	v_permlane32_swap_b32_e32 v248, v249
	v_max_f32_e32 v249, v249, v249
	v_max_f32_e32 v248, v248, v248
	v_max_f32_e32 v248, v248, v249
	v_max_f32_e32 v250, v208, v208
	ds_read_b64_tr_b16 v[224:225], v185 offset:0x400
	ds_read_b64_tr_b16 v[226:227], v185 offset:0xc00
	v_mfma_f32_32x32x16_bf16 v[18:33], v[220:223], v[228:231], v[18:33]
	v_sub_f32_e32 v249, v248, v208
	v_max_f32_e32 v248, v250, v248
	v_sub_f32_e32 v250, v208, v248
	v_mul_f32_e32 v250, 0x3e0293ee, v250
	v_exp_f32_e32 v250, v250
	ds_read_b64_tr_b16 v[228:229], v185 offset:0x1400
	ds_read_b64_tr_b16 v[230:231], v185 offset:0x1c00
	v_mfma_f32_32x32x16_bf16 v[18:33], v[212:215], v[232:235], v[18:33]
	v_cmp_ge_f32_e32 vcc, s48, v249
	s_cmp_eq_u64 vcc, exec
	s_cselect_b64 s[4:5], -1, 0
	ds_read_b64_tr_b16 v[232:233], v185 offset:0x2400
	ds_read_b64_tr_b16 v[234:235], v185 offset:0x2c00
	ds_read_b64_tr_b16 v[236:237], v185 offset:0x3400
	ds_read_b64_tr_b16 v[238:239], v185 offset:0x3c00
	s_waitcnt lgkmcnt(0)
	v_mfma_f32_32x32x16_bf16 v[18:33], v[216:219], v[240:243], v[18:33]
	v_cndmask_b32_e64 v249, v250, 1.0, s[4:5]
	v_cndmask_b32_e64 v251, v248, v208, s[4:5]
	v_mul_f32_e32 v248, 0xbe0293ee, v251
	v_mfma_f32_32x32x16_bf16 v[50:65], v[162:165], v[224:227], v[50:65]
	v_fmamk_f32 v82, v82, 0x3e0293ee, v248
	v_fmamk_f32 v83, v83, 0x3e0293ee, v248
	v_fmamk_f32 v84, v84, 0x3e0293ee, v248
	ds_read_b64_tr_b16 v[224:225], v185 offset:0x600
	ds_read_b64_tr_b16 v[226:227], v185 offset:0xe00
	v_mfma_f32_32x32x16_bf16 v[50:65], v[220:223], v[228:231], v[50:65]
	v_fmamk_f32 v85, v85, 0x3e0293ee, v248
	v_fmamk_f32 v86, v86, 0x3e0293ee, v248
	v_fmamk_f32 v87, v87, 0x3e0293ee, v248
	ds_read_b64_tr_b16 v[228:229], v185 offset:0x1600
	ds_read_b64_tr_b16 v[230:231], v185 offset:0x1e00
	v_mfma_f32_32x32x16_bf16 v[50:65], v[212:215], v[232:235], v[50:65]
	v_fmamk_f32 v88, v88, 0x3e0293ee, v248
	v_fmamk_f32 v89, v89, 0x3e0293ee, v248
	ds_read_b64_tr_b16 v[232:233], v185 offset:0x2600
	ds_read_b64_tr_b16 v[234:235], v185 offset:0x2e00
	ds_read_b64_tr_b16 v[240:241], v185 offset:0x3600
	ds_read_b64_tr_b16 v[242:243], v185 offset:0x3e00
	s_waitcnt lgkmcnt(0)
	v_mfma_f32_32x32x16_bf16 v[50:65], v[216:219], v[236:239], v[50:65]
	v_fmamk_f32 v90, v90, 0x3e0293ee, v248
	v_fmamk_f32 v91, v91, 0x3e0293ee, v248
	v_mfma_f32_32x32x16_bf16 v[34:49], v[162:165], v[224:227], v[34:49]
	v_fmamk_f32 v92, v92, 0x3e0293ee, v248
	v_fmamk_f32 v93, v93, 0x3e0293ee, v248
	v_mfma_f32_32x32x16_bf16 v[34:49], v[220:223], v[228:231], v[34:49]
	v_fmamk_f32 v94, v94, 0x3e0293ee, v248
	v_fmamk_f32 v95, v95, 0x3e0293ee, v248
	v_mfma_f32_32x32x16_bf16 v[34:49], v[212:215], v[232:235], v[34:49]
	v_fmamk_f32 v96, v96, 0x3e0293ee, v248
	v_fmamk_f32 v97, v97, 0x3e0293ee, v248
	v_mfma_f32_32x32x16_bf16 v[34:49], v[216:219], v[240:243], v[34:49]
	s_barrier
	s_waitcnt vmcnt(4)
	v_mov_b32_e32 v163, v249
	v_mov_b32_e32 v164, v251
	v_mov_b32_e32 v162, v248
	v_cmp_gt_f32_e32 vcc, 1.0, v163
	s_waitcnt vmcnt(7)
	ds_write_b128 v191, v[130:133]
	s_waitcnt vmcnt(5)
	ds_write_b128 v192, v[142:145]
	ds_write_b128 v193, v[134:137] offset:32768
	s_waitcnt vmcnt(4)
	ds_write_b128 v194, v[138:141] offset:32768
	s_cbranch_vccz .LBB0_1590
	s_and_saveexec_b64 s[40:41], s[2:3]
	ds_write_b32 v187, v163 offset:128
	s_or_b64 exec, exec, s[40:41]
	s_waitcnt lgkmcnt(0)
	v_add_u32_e32 v142, v182, v186
	ds_read_b128 v[130:133], v142 offset:224
	ds_read_b128 v[134:137], v142 offset:192
	ds_read_b128 v[138:141], v142 offset:160
	ds_read_b128 v[142:145], v142 offset:128
	s_waitcnt lgkmcnt(3)
	v_pk_mul_f32 v[14:15], v[14:15], v[130:131]
	s_waitcnt lgkmcnt(2)
	v_pk_mul_f32 v[10:11], v[10:11], v[134:135]
	s_waitcnt lgkmcnt(1)
	v_pk_mul_f32 v[6:7], v[6:7], v[138:139]
	v_pk_mul_f32 v[16:17], v[16:17], v[132:133]
	v_pk_mul_f32 v[12:13], v[12:13], v[136:137]
	v_pk_mul_f32 v[8:9], v[8:9], v[140:141]
	s_waitcnt lgkmcnt(0)
	v_pk_mul_f32 v[4:5], v[4:5], v[144:145]
	v_pk_mul_f32 v[2:3], v[2:3], v[142:143]
	v_pk_mul_f32 v[30:31], v[30:31], v[130:131]
	v_pk_mul_f32 v[26:27], v[26:27], v[134:135]
	v_pk_mul_f32 v[22:23], v[22:23], v[138:139]
	v_pk_mul_f32 v[32:33], v[32:33], v[132:133]
	v_pk_mul_f32 v[28:29], v[28:29], v[136:137]
	v_pk_mul_f32 v[24:25], v[24:25], v[140:141]
	v_pk_mul_f32 v[20:21], v[20:21], v[144:145]
	v_pk_mul_f32 v[18:19], v[18:19], v[142:143]
	v_pk_mul_f32 v[62:63], v[62:63], v[130:131]
	v_pk_mul_f32 v[58:59], v[58:59], v[134:135]
	v_pk_mul_f32 v[54:55], v[54:55], v[138:139]
	v_pk_mul_f32 v[64:65], v[64:65], v[132:133]
	v_pk_mul_f32 v[60:61], v[60:61], v[136:137]
	v_pk_mul_f32 v[56:57], v[56:57], v[140:141]
	v_pk_mul_f32 v[52:53], v[52:53], v[144:145]
	v_pk_mul_f32 v[50:51], v[50:51], v[142:143]
	v_pk_mul_f32 v[46:47], v[46:47], v[130:131]
	v_pk_mul_f32 v[42:43], v[42:43], v[134:135]
	v_pk_mul_f32 v[38:39], v[38:39], v[138:139]
	v_pk_mul_f32 v[48:49], v[48:49], v[132:133]
	v_pk_mul_f32 v[44:45], v[44:45], v[136:137]
	v_pk_mul_f32 v[40:41], v[40:41], v[140:141]
	v_pk_mul_f32 v[36:37], v[36:37], v[144:145]
	v_pk_mul_f32 v[34:35], v[34:35], v[142:143]

; #define SBAR() __builtin_amdgcn_sched_barrier(0)
; #define SWAIT() do { if constexpr (SDEPTH == 2) asm volatile("s_waitcnt vmcnt(4)" ::: "memory"); else asm volatile("s_waitcnt vmcnt(0)" ::: "memory"); } while (0)
; __device__ __forceinline__ void partialSM(f32x16& p0, f32x16& p1, float& m_reg, float& mn, float& alpha) {
;     ...
;   for (int r = 0; r < 16; ++r) p0[r] = fmaf(p0[r], C, mnC); for (int r = 0; r < 16; ++r) p1[r] = fmaf(p1[r], C, mnC);
;   for (int r = 0; r < 16; ++r) p0[r] = __builtin_amdgcn_exp2f(p0[r]);
; }
; __device__ __forceinline__ void finishSM(f32x16& p0, f32x16& p1, float alpha, float& l_reg, bf16x8& pa0, bf16x8& pa1, bf16x8& pa2, bf16x8& pa3) {
;   for (int r = 0; r < 16; ++r) p1[r] = __builtin_amdgcn_exp2f(p1[r]);
;   float ps = 0; for (int r = 0; r < 16; ++r) ps += p0[r]; for (int r = 0; r < 16; ++r) ps += p1[r];
;   { auto rr = __builtin_amdgcn_permlane32_swap(__float_as_uint(ps), __float_as_uint(ps), false, false);
;     ps = __uint_as_float(rr[0]) + __uint_as_float(rr[1]); }
;   l_reg = l_reg * alpha + ps;
;     ...
;   PK4(p0, 0, pa0); PK4(p0, 8, pa1); PK4(p1, 0, pa2); PK4(p1, 8, pa3);
;     ...
; }
; __device__ __forceinline__ void qkt(f32x16& p0, f32x16& p1, const bf16* Ks, const bf16x8* qr, int r32, int hi) {
;   p0 = f32x16{}; p1 = f32x16{};
;   for (int d0 = 0; d0 < 8; ++d0) { int cb = (d0 * 16 + hi * 8) * 2;
;     bf16x8 b0 = *reinterpret_cast<const bf16x8*>((const char*)Ks + KSWZ(r32, cb));
;     bf16x8 b1 = *reinterpret_cast<const bf16x8*>((const char*)Ks + KSWZ(32 + r32, cb));
;     p0 = __builtin_amdgcn_mfma_f32_32x32x16_bf16(b0, qr[d0], p0, 0, 0, 0);
;     p1 = __builtin_amdgcn_mfma_f32_32x32x16_bf16(b1, qr[d0], p1, 0, 0, 0); }
; template <typename TQ>
; __device__ __forceinline__ void attn_dense_body(const TQ* __restrict__ Qb, const bf16* __restrict__ Kh, const bf16* __restrict__ Vh,
;                                                 unsigned short* __restrict__ Ob, int seq, char* lds) {
;     ...
;     pv_d0(o, vb0 + (int)SHM_V, pa0, pa1, pa2, pa3); partialSM(pA0, pA1, m_reg, mnA, alA);
;     __syncthreads(); SWAIT(); SWRITE(1, SO);
;     RESC(alA); __syncthreads();
;   }
;   SBAR(); qkt(pB0, pB1, (bf16*)((char*)K_lds + SHM_K), qr, r32, hi);
;   finishSM(pA0, pA1, alA, l_reg, pa0, pa1, pa2, pa3); SBAR();
.LBB0_1594:
	v_mov_b32_e32 v152, v224
	v_exp_f32_e32 v224, v82
	v_exp_f32_e32 v226, v83
	v_exp_f32_e32 v222, v84
	v_exp_f32_e32 v225, v85
	v_exp_f32_e32 v164, v86
	v_exp_f32_e32 v223, v87
	v_exp_f32_e32 v220, v88
	v_exp_f32_e32 v221, v89
	v_exp_f32_e32 v217, v90
	v_exp_f32_e32 v219, v91
	v_exp_f32_e32 v216, v92
	v_exp_f32_e32 v218, v93
	v_exp_f32_e32 v213, v94
	v_exp_f32_e32 v215, v95
	v_exp_f32_e32 v212, v96
	v_exp_f32_e32 v214, v97
	v_pk_fma_f32 v[156:157], v[66:67], s[30:31], v[152:153] op_sel_hi:[1,0,0]
	v_add_f32_e32 v66, v209, v210
	s_add_i32 s68, s68, 2
	s_addk_i32 s67, 0x80
	v_fmac_f32_e32 v66, v177, v175
	v_add_f32_e32 v175, v165, v211
	s_add_u32 s38, s38, 0x8000
	v_pk_fma_f32 v[154:155], v[68:69], s[30:31], v[152:153] op_sel_hi:[1,0,0]
	v_pk_fma_f32 v[150:151], v[70:71], s[30:31], v[152:153] op_sel_hi:[1,0,0]
	v_pk_fma_f32 v[148:149], v[72:73], s[30:31], v[152:153] op_sel_hi:[1,0,0]
	v_pk_fma_f32 v[146:147], v[74:75], s[30:31], v[152:153] op_sel_hi:[1,0,0]
	v_pk_fma_f32 v[160:161], v[76:77], s[30:31], v[152:153] op_sel_hi:[1,0,0]
	v_pk_fma_f32 v[158:159], v[78:79], s[30:31], v[152:153] op_sel_hi:[1,0,0]
	v_pk_fma_f32 v[152:153], v[80:81], s[30:31], v[152:153] op_sel_hi:[1,0,0]
	v_fmac_f32_e32 v175, v66, v163
	s_addc_u32 s39, s39, 0
	s_and_b64 vcc, exec, s[40:41]
	s_waitcnt lgkmcnt(0)
	s_cbranch_vccnz .Lattn_exit
	v_mov_b32_e32 v177, v162
	s_branch .Lattn_head
.Lattn_exit:
	s_barrier
.LBB0_1596:
	ds_read_b128 v[66:69], v195 offset:49152
	ds_read_b128 v[70:73], v195 offset:57344
	v_exp_f32_e32 v156, v156
	v_exp_f32_e32 v157, v157
	v_exp_f32_e32 v154, v154
	s_waitcnt lgkmcnt(1)
	v_mfma_f32_32x32x16_bf16 v[82:97], v[66:69], v[126:129], 0
	v_exp_f32_e32 v155, v155
	v_exp_f32_e32 v150, v150
	s_waitcnt lgkmcnt(0)
	v_mfma_f32_32x32x16_bf16 v[66:81], v[70:73], v[126:129], 0
	ds_read_b128 v[126:129], v196 offset:49152
	s_waitcnt vmcnt(3)
	ds_read_b128 v[130:133], v196 offset:57344
	s_waitcnt vmcnt(2)
	ds_read_b128 v[134:137], v197 offset:49152
	s_waitcnt vmcnt(0)
	ds_read_b128 v[138:141], v197 offset:57344
	s_waitcnt lgkmcnt(3)
	v_mfma_f32_32x32x16_bf16 v[82:97], v[126:129], v[122:125], v[82:97]
	ds_read_b128 v[126:129], v198 offset:49152
	ds_read_b128 v[142:145], v198 offset:57344
	ds_read_b128 v[228:231], v199 offset:49152
	ds_read_b128 v[232:235], v199 offset:57344
	ds_read_b128 v[236:239], v200 offset:49152
	ds_read_b128 v[240:243], v200 offset:57344
	ds_read_b128 v[244:247], v201 offset:49152
	ds_read_b128 v[248:251], v201 offset:57344
	s_waitcnt lgkmcnt(10)
	v_mfma_f32_32x32x16_bf16 v[66:81], v[130:133], v[122:125], v[66:81]
	ds_read_b128 v[122:125], v202 offset:49152
	ds_read_b128 v[130:133], v202 offset:57344
	s_waitcnt lgkmcnt(11)
	v_mfma_f32_32x32x16_bf16 v[82:97], v[134:137], v[118:121], v[82:97]
	v_exp_f32_e32 v134, v151
	v_exp_f32_e32 v135, v148
	v_exp_f32_e32 v136, v149
	v_exp_f32_e32 v137, v146
	v_exp_f32_e32 v146, v147
	v_exp_f32_e32 v147, v160
	v_exp_f32_e32 v148, v161
	s_waitcnt lgkmcnt(10)
	v_mfma_f32_32x32x16_bf16 v[66:81], v[138:141], v[118:121], v[66:81]
	v_add_f32_e32 v118, 0, v224
	v_add_f32_e32 v118, v226, v118
	v_add_f32_e32 v118, v222, v118
	v_add_f32_e32 v118, v225, v118
	v_add_f32_e32 v118, v164, v118
	v_add_f32_e32 v118, v223, v118
	v_add_f32_e32 v118, v220, v118
	s_waitcnt lgkmcnt(9)
	v_mfma_f32_32x32x16_bf16 v[82:97], v[126:129], v[114:117], v[82:97]
	v_add_f32_e32 v118, v221, v118
	v_add_f32_e32 v118, v217, v118
	v_add_f32_e32 v118, v219, v118
	v_exp_f32_e32 v120, v158
	v_exp_f32_e32 v121, v159
	v_exp_f32_e32 v138, v152
	v_exp_f32_e32 v139, v153
	s_waitcnt lgkmcnt(8)
	v_mfma_f32_32x32x16_bf16 v[66:81], v[142:145], v[114:117], v[66:81]
	v_add_f32_e32 v114, v216, v118
	v_add_f32_e32 v114, v218, v114
	v_add_f32_e32 v114, v213, v114
	v_add_f32_e32 v114, v215, v114
	v_add_f32_e32 v114, v212, v114
	v_add_f32_e32 v114, v214, v114
	v_add_f32_e32 v114, v156, v114
	s_waitcnt lgkmcnt(7)
	v_mfma_f32_32x32x16_bf16 v[82:97], v[228:231], v[110:113], v[82:97]
	v_add_f32_e32 v114, v157, v114
	v_add_f32_e32 v114, v154, v114
	v_add_f32_e32 v114, v155, v114
	v_add_f32_e32 v114, v150, v114
	v_add_f32_e32 v114, v134, v114
	v_add_f32_e32 v114, v135, v114
	v_add_f32_e32 v114, v136, v114
	s_waitcnt lgkmcnt(6)
	v_mfma_f32_32x32x16_bf16 v[66:81], v[232:235], v[110:113], v[66:81]
	v_add_f32_e32 v110, v137, v114
	v_add_f32_e32 v110, v146, v110
	v_add_f32_e32 v110, v147, v110
	v_add_f32_e32 v110, v148, v110
	v_add_f32_e32 v110, v120, v110
	v_add_f32_e32 v110, v121, v110
	v_add_f32_e32 v110, v138, v110
	s_waitcnt lgkmcnt(5)
	v_mfma_f32_32x32x16_bf16 v[82:97], v[236:239], v[106:109], v[82:97]
	v_add_f32_e32 v110, v139, v110
	v_mov_b32_e32 v111, v110
	s_nop 1
	v_permlane32_swap_b32_e32 v110, v111
	v_cvt_pk_bf16_f32 v112, v224, v226
	v_cvt_pk_bf16_f32 v113, v222, v225
	v_cvt_pk_bf16_f32 v114, v164, v223
	s_waitcnt lgkmcnt(4)
	v_mfma_f32_32x32x16_bf16 v[66:81], v[240:243], v[106:109], v[66:81]
	v_cvt_pk_bf16_f32 v115, v220, v221
	v_cvt_pk_bf16_f32 v106, v217, v219
	v_cvt_pk_bf16_f32 v107, v216, v218
	v_cvt_pk_bf16_f32 v108, v213, v215
	v_cvt_pk_bf16_f32 v109, v212, v214
	v_cvt_pk_bf16_f32 v116, v156, v157
	v_cvt_pk_bf16_f32 v117, v154, v155
	s_waitcnt lgkmcnt(3)
	v_mfma_f32_32x32x16_bf16 v[82:97], v[244:247], v[102:105], v[82:97]
	v_cvt_pk_bf16_f32 v118, v150, v134
	v_cvt_pk_bf16_f32 v119, v135, v136
	v_permlane32_swap_b32_e32 v112, v114
	v_permlane32_swap_b32_e32 v113, v115
	v_permlane32_swap_b32_e32 v106, v108
	s_waitcnt lgkmcnt(2)
	v_mfma_f32_32x32x16_bf16 v[66:81], v[248:251], v[102:105], v[66:81]
	v_cvt_pk_bf16_f32 v102, v137, v146
	v_cvt_pk_bf16_f32 v103, v147, v148
	v_cvt_pk_bf16_f32 v104, v120, v121
	v_cvt_pk_bf16_f32 v105, v138, v139
	v_permlane32_swap_b32_e32 v107, v109
	v_permlane32_swap_b32_e32 v116, v118
	s_waitcnt lgkmcnt(1)
; __device__ __forceinline__ void partialSM(f32x16& p0, f32x16& p1, float& m_reg, float& mn, float& alpha) {
;   constexpr float C = SCALE * 1.4426950408889634f;
;   float pmax = p0[0]; for (int r = 1; r < 16; ++r) pmax = fmaxf(pmax, p0[r]); for (int r = 0; r < 16; ++r) pmax = fmaxf(pmax, p1[r]);
;   { auto rr = __builtin_amdgcn_permlane32_swap(__float_as_uint(pmax), __float_as_uint(pmax), false, false);
;     pmax = fmaxf(__uint_as_float(rr[0]), __uint_as_float(rr[1])); }
;   if (__builtin_expect(__all(pmax - m_reg <= THR / SCALE), 1)) { mn = m_reg; alpha = 1.f; }
;   else { mn = fmaxf(m_reg, pmax); alpha = __builtin_amdgcn_exp2f((m_reg - mn) * C); m_reg = mn; }
;   float mnC = -mn * C;
;   for (int r = 0; r < 16; ++r) p0[r] = fmaf(p0[r], C, mnC); for (int r = 0; r < 16; ++r) p1[r] = fmaf(p1[r], C, mnC);
;   for (int r = 0; r < 16; ++r) p0[r] = __builtin_amdgcn_exp2f(p0[r]);
; }
; __device__ __forceinline__ void finishSM(f32x16& p0, f32x16& p1, float alpha, float& l_reg, bf16x8& pa0, bf16x8& pa1, bf16x8& pa2, bf16x8& pa3) {
;   for (int r = 0; r < 16; ++r) p1[r] = __builtin_amdgcn_exp2f(p1[r]);
;   float ps = 0; for (int r = 0; r < 16; ++r) ps += p0[r]; for (int r = 0; r < 16; ++r) ps += p1[r];
;   { auto rr = __builtin_amdgcn_permlane32_swap(__float_as_uint(ps), __float_as_uint(ps), false, false);
;     ps = __uint_as_float(rr[0]) + __uint_as_float(rr[1]); }
;   l_reg = l_reg * alpha + ps;
;     ...
;   PK4(p0, 0, pa0); PK4(p0, 8, pa1); PK4(p1, 0, pa2); PK4(p1, 8, pa3);
;     ...
; }
; __device__ __forceinline__ void qkt(f32x16& p0, f32x16& p1, const bf16* Ks, const bf16x8* qr, int r32, int hi) {
;   p0 = f32x16{}; p1 = f32x16{};
;   for (int d0 = 0; d0 < 8; ++d0) { int cb = (d0 * 16 + hi * 8) * 2;
;     bf16x8 b0 = *reinterpret_cast<const bf16x8*>((const char*)Ks + KSWZ(r32, cb));
;     bf16x8 b1 = *reinterpret_cast<const bf16x8*>((const char*)Ks + KSWZ(32 + r32, cb));
;     p0 = __builtin_amdgcn_mfma_f32_32x32x16_bf16(b0, qr[d0], p0, 0, 0, 0);
;     p1 = __builtin_amdgcn_mfma_f32_32x32x16_bf16(b1, qr[d0], p1, 0, 0, 0); }
; }
; __device__ __forceinline__ int v_st(int k, int c) { const int kk = (k & ~0xC) | ((k & 4) << 1) | ((k & 8) >> 1); return ((kk >> 3) * 4 + (c >> 5)) * 512 + ((kk & 7) * 32 + (c & 31)) * 2; }
; __device__ __forceinline__ int v_rd_base(int lane) { return ((lane & 3) << 3) | (((lane >> 2) & 3) << 6) | (((lane >> 4) & 1) << 5) | (((lane >> 5) & 1) << 8); }
	v_mfma_f32_32x32x16_bf16 v[82:97], v[122:125], v[98:101], v[82:97]
	v_permlane32_swap_b32_e32 v117, v119
	v_permlane32_swap_b32_e32 v102, v104
	v_permlane32_swap_b32_e32 v103, v105
	s_waitcnt lgkmcnt(0)
	v_mfma_f32_32x32x16_bf16 v[66:81], v[130:133], v[98:101], v[66:81]
	ds_read_b64_tr_b16 v[98:99], v185 offset:0
	ds_read_b64_tr_b16 v[100:101], v185 offset:0x800
	ds_read_b64_tr_b16 v[120:121], v185 offset:0x1000
	ds_read_b64_tr_b16 v[122:123], v185 offset:0x1800
	ds_read_b64_tr_b16 v[124:125], v185 offset:0x2000
	ds_read_b64_tr_b16 v[126:127], v185 offset:0x2800
	ds_read_b64_tr_b16 v[128:129], v185 offset:0x3000
	ds_read_b64_tr_b16 v[130:131], v185 offset:0x3800
	s_waitcnt lgkmcnt(0)
	s_nop 0
	v_mfma_f32_32x32x16_bf16 v[2:17], v[112:115], v[98:101], v[2:17]
	ds_read_b64_tr_b16 v[98:99], v185 offset:0x200
	ds_read_b64_tr_b16 v[100:101], v185 offset:0xa00
	v_mfma_f32_32x32x16_bf16 v[2:17], v[106:109], v[120:123], v[2:17]
	ds_read_b64_tr_b16 v[120:121], v185 offset:0x1200
	ds_read_b64_tr_b16 v[122:123], v185 offset:0x1a00
	v_mfma_f32_32x32x16_bf16 v[2:17], v[116:119], v[124:127], v[2:17]
	ds_read_b64_tr_b16 v[124:125], v185 offset:0x2200
	ds_read_b64_tr_b16 v[126:127], v185 offset:0x2a00
	ds_read_b64_tr_b16 v[132:133], v185 offset:0x3200
	ds_read_b64_tr_b16 v[134:135], v185 offset:0x3a00
	s_waitcnt lgkmcnt(0)
	v_mfma_f32_32x32x16_bf16 v[2:17], v[102:105], v[128:131], v[2:17]
	v_mfma_f32_32x32x16_bf16 v[18:33], v[112:115], v[98:101], v[18:33]
	ds_read_b64_tr_b16 v[98:99], v185 offset:0x400
	ds_read_b64_tr_b16 v[100:101], v185 offset:0xc00
	v_mfma_f32_32x32x16_bf16 v[18:33], v[106:109], v[120:123], v[18:33]
	ds_read_b64_tr_b16 v[120:121], v185 offset:0x1400
	ds_read_b64_tr_b16 v[122:123], v185 offset:0x1c00
	v_mfma_f32_32x32x16_bf16 v[18:33], v[116:119], v[124:127], v[18:33]
	ds_read_b64_tr_b16 v[124:125], v185 offset:0x2400
	ds_read_b64_tr_b16 v[126:127], v185 offset:0x2c00
	ds_read_b64_tr_b16 v[128:129], v185 offset:0x3400
	ds_read_b64_tr_b16 v[130:131], v185 offset:0x3c00
	s_waitcnt lgkmcnt(0)
	v_mfma_f32_32x32x16_bf16 v[18:33], v[102:105], v[132:135], v[18:33]
	v_mfma_f32_32x32x16_bf16 v[50:65], v[112:115], v[98:101], v[50:65]
	ds_read_b64_tr_b16 v[98:99], v185 offset:0x600
	ds_read_b64_tr_b16 v[100:101], v185 offset:0xe00
	v_mfma_f32_32x32x16_bf16 v[50:65], v[106:109], v[120:123], v[50:65]
	ds_read_b64_tr_b16 v[120:121], v185 offset:0x1600
	ds_read_b64_tr_b16 v[122:123], v185 offset:0x1e00
	v_mfma_f32_32x32x16_bf16 v[50:65], v[116:119], v[124:127], v[50:65]
	ds_read_b64_tr_b16 v[124:125], v185 offset:0x2600
	ds_read_b64_tr_b16 v[126:127], v185 offset:0x2e00
	ds_read_b64_tr_b16 v[132:133], v185 offset:0x3600
	ds_read_b64_tr_b16 v[134:135], v185 offset:0x3e00
	s_waitcnt lgkmcnt(0)
	v_mfma_f32_32x32x16_bf16 v[50:65], v[102:105], v[128:131], v[50:65]
	v_mfma_f32_32x32x16_bf16 v[34:49], v[112:115], v[98:101], v[34:49]
	v_max_f32_e32 v128, v83, v83
	v_max_f32_e32 v129, v82, v82
	v_max_f32_e32 v128, v129, v128
	v_max3_f32 v128, v128, v84, v85
	v_max3_f32 v128, v128, v86, v87
	v_max3_f32 v98, v128, v88, v89
	v_max3_f32 v98, v98, v90, v91
	v_max3_f32 v98, v98, v92, v93
	v_mfma_f32_32x32x16_bf16 v[34:49], v[106:109], v[120:123], v[34:49]
	v_max3_f32 v98, v98, v94, v95
	v_max3_f32 v98, v98, v96, v97
	v_max3_f32 v98, v98, v66, v67
	v_max3_f32 v98, v98, v68, v69
	v_max3_f32 v98, v98, v70, v71
	v_max3_f32 v98, v98, v72, v73
	v_max3_f32 v98, v98, v74, v75
	v_max3_f32 v98, v98, v76, v77
	v_mfma_f32_32x32x16_bf16 v[34:49], v[116:119], v[124:127], v[34:49]
	v_max3_f32 v98, v98, v78, v79
	v_max3_f32 v98, v98, v80, v81
	v_mov_b32_e32 v99, v98
	s_nop 1
	v_permlane32_swap_b32_e32 v98, v99
	v_max_f32_e32 v99, v99, v99
	v_max_f32_e32 v98, v98, v98
	v_max_f32_e32 v98, v98, v99
	v_max_f32_e32 v99, v208, v208
	v_max_f32_e32 v99, v99, v98
	v_sub_f32_e32 v100, v98, v208
	v_mfma_f32_32x32x16_bf16 v[34:49], v[102:105], v[132:135], v[34:49]
	v_sub_f32_e32 v98, v208, v99
	v_mul_f32_e32 v98, 0x3e0293ee, v98
	v_exp_f32_e32 v98, v98
	v_cmp_ge_f32_e32 vcc, s48, v100
	s_cmp_eq_u64 vcc, exec
	s_cselect_b64 s[4:5], -1, 0
	v_cndmask_b32_e64 v98, v98, 1.0, s[4:5]
	v_cmp_gt_f32_e32 vcc, 1.0, v98
	s_barrier
	s_cbranch_vccz .LBB0_1600
	s_and_saveexec_b64 s[34:35], s[2:3]
	ds_write_b32 v187, v98 offset:128
	s_or_b64 exec, exec, s[34:35]
	s_waitcnt lgkmcnt(0)
	v_add_u32_e32 v108, v182, v186
	ds_read_b128 v[100:103], v108 offset:224
	ds_read_b128 v[104:107], v108 offset:192
	ds_read_b128 v[112:115], v108 offset:160
	ds_read_b128 v[116:119], v108 offset:128
	s_waitcnt lgkmcnt(3)
	v_pk_mul_f32 v[14:15], v[14:15], v[100:101]
	s_waitcnt lgkmcnt(2)
	v_pk_mul_f32 v[10:11], v[10:11], v[104:105]
	s_waitcnt lgkmcnt(1)
	v_pk_mul_f32 v[6:7], v[6:7], v[112:113]
	v_pk_mul_f32 v[16:17], v[16:17], v[102:103]
	v_pk_mul_f32 v[12:13], v[12:13], v[106:107]
	v_pk_mul_f32 v[8:9], v[8:9], v[114:115]
	s_waitcnt lgkmcnt(0)
	v_pk_mul_f32 v[4:5], v[4:5], v[118:119]
	v_pk_mul_f32 v[2:3], v[2:3], v[116:117]
	v_pk_mul_f32 v[30:31], v[30:31], v[100:101]
	v_pk_mul_f32 v[26:27], v[26:27], v[104:105]
	v_pk_mul_f32 v[22:23], v[22:23], v[112:113]
	v_pk_mul_f32 v[32:33], v[32:33], v[102:103]
	v_pk_mul_f32 v[28:29], v[28:29], v[106:107]
	v_pk_mul_f32 v[24:25], v[24:25], v[114:115]
	v_pk_mul_f32 v[20:21], v[20:21], v[118:119]
	v_pk_mul_f32 v[18:19], v[18:19], v[116:117]
	v_pk_mul_f32 v[62:63], v[62:63], v[100:101]
	v_pk_mul_f32 v[58:59], v[58:59], v[104:105]
	v_pk_mul_f32 v[54:55], v[54:55], v[112:113]
	v_pk_mul_f32 v[64:65], v[64:65], v[102:103]
	v_pk_mul_f32 v[60:61], v[60:61], v[106:107]
	v_pk_mul_f32 v[56:57], v[56:57], v[114:115]
	v_pk_mul_f32 v[52:53], v[52:53], v[118:119]
	v_pk_mul_f32 v[50:51], v[50:51], v[116:117]
	v_pk_mul_f32 v[46:47], v[46:47], v[100:101]
	v_pk_mul_f32 v[42:43], v[42:43], v[104:105]
	v_pk_mul_f32 v[38:39], v[38:39], v[112:113]
	v_pk_mul_f32 v[48:49], v[48:49], v[102:103]
	v_pk_mul_f32 v[44:45], v[44:45], v[106:107]
	v_pk_mul_f32 v[40:41], v[40:41], v[114:115]
	v_pk_mul_f32 v[36:37], v[36:37], v[118:119]
	v_pk_mul_f32 v[34:35], v[34:35], v[116:117]
